# EpiProj: straight-line path for k_B / v_B panels with f32 cache side outputs (sample rows and the last two prompt panels of a sequence)
# baseline (speedup 1.0000x reference)
;     DI void operator()(f32x4 (&acc)[2][2][4][2], const Unit& u, int wr, int wc, int fr, int fq, LAS unsigned char* lds) const {
;     ...
;                     const int gcol = u.pn * 256 + bj * 128;
;                     f32x4 v0 = acc[ai][bj][m][0] * rs, v1 = acc[ai][bj][m][1] * rs;
;                     if (gcol < 768 && gcol != 640) {
;                         if (rope_wave) {
;                             const float* rp = ROPE + (size_t)posidx * 16;
;                             const f32x4 cs0 = *(const f32x4*)rp, cs1 = *(const f32x4*)(rp + 4), sn0 = *(const f32x4*)(rp + 8), sn1 = *(const f32x4*)(rp + 12);
;                             f32x4 p0, p1;
; #pragma unroll
;                             for (int j = 0; j < 4; ++j) { p0[j] = __shfl_xor(v0[j], 16); p1[j] = __shfl_xor(v1[j], 16); }
;                             if (fq == 0) { v0 = v0 * cs0 - p0 * sn0; v1 = v1 * cs1 - p1 * sn1; }
;                             else if (fq == 1) { v0 = v0 * cs0 + p0 * sn0; v1 = v1 * cs1 + p1 * sn1; }
;                         }
;                     }
;                     bf16_t* dst; int ld, c0; float* of = nullptr; long orow = -1;
;                     if (gcol < 512) { dst = QA; ld = 512; c0 = gcol; v0 = v0 * QSCALE; v1 = v1 * QSCALE; }
;                     else if (gcol < 640) { dst = KA; ld = 128; c0 = gcol - 512; of = out + (prm ? O_KWP : O_KWS); orow = offA; }
;                     else if (gcol < 768) { dst = VA; ld = 128; c0 = gcol - 640; of = out + (prm ? O_VWP : O_VWS); orow = offA; }
;                     else if (gcol < 1280) { dst = QB; ld = 512; c0 = gcol - 768; v0 = v0 * QSCALE; v1 = v1 * QSCALE; }
;                     else if (gcol < 1792) { dst = KB; ld = 512; c0 = gcol - 1280; of = out + (prm ? O_KBP : O_KBS); orow = offB; }
;                     else if (gcol < 2304) { dst = VB; ld = 512; c0 = gcol - 1792; of = out + (prm ? O_VBP : O_VBS); orow = offB; }
;                     else { dst = GATES; ld = 2048; c0 = gcol - 2304;
;                         const f32x4 g0 = *(const LAS f32x4*)(lds + BG_OFF + (c0 + cw) * 4), g1 = *(const LAS f32x4*)(lds + BG_OFF + (c0 + cw + 4) * 4);
; #pragma unroll
;                         for (int j = 0; j < 4; ++j) { v0[j] = sigmoidf_(v0[j] + g0[j]); v1[j] = sigmoidf_(v1[j] + g1[j]); } }
;                     u32x4 w; w.x = pk2(v0[0], v0[1]); w.y = pk2(v0[2], v0[3]); w.z = pk2(v1[0], v1[1]); w.w = pk2(v1[2], v1[3]);
.Lrope_pre_skip:
	v_lshl_add_u32 v96, s4, 10, v175
	ds_read2_b32 v[220:221], v96 offset1:16
	ds_read2_b32 v[204:205], v96 offset0:32 offset1:48
	ds_read2_b32 v[198:199], v96 offset0:128 offset1:144
	ds_read2_b32 v[194:195], v96 offset0:160 offset1:176
	v_lshl_add_u32 v192, s96, 8, v171
	s_cmp_gt_i32 s97, 8
	s_cbranch_scc1 .Lepf_gates
	s_cmp_lt_i32 s97, 2
	s_cbranch_scc1 .Lepf_qa
	s_cmp_lt_i32 s97, 3
	s_cbranch_scc1 .Lepf_none
	s_cmp_lt_i32 s97, 5
	s_cbranch_scc1 .Lepf_qb
	s_cmp_lt_i32 s97, 7
	s_cbranch_scc1 .Lepf_kb
	v_readlane_b32 s24, v250, 42
	v_readlane_b32 s25, v250, 43
	s_add_i32 s22, s97, -7
	s_lshl_b32 s22, s22, 9
	s_mov_b32 s26, 0x2440000
	s_mov_b32 s27, 0x3840000
	s_branch .Lepf_kv2
.Lepf_kb:
	v_readlane_b32 s24, v250, 46
	v_readlane_b32 s25, v250, 47
	s_add_i32 s22, s97, -5
	s_lshl_b32 s22, s22, 9
	s_mov_b32 s26, 0x2240000
	s_mov_b32 s27, 0x2840000
.Lepf_kv2:
	s_cmpk_gt_i32 s96, 0x7f
	s_cbranch_scc1 .Lepf_kv_sample
	s_and_b32 s0, s96, 31
	s_cmp_gt_i32 s0, 29
	s_cbranch_scc1 .Lepf_kv_tail
	s_waitcnt lgkmcnt(0)
	v_lshlrev_b32_e32 v154, 10, v192
	v_lshl_add_u32 v154, v166, 1, v154
	v_add_u32_e32 v154, s22, v154
	v_mul_f32_e32 v146, v126, v220
	v_mul_f32_e32 v147, v127, v220
	v_mul_f32_e32 v148, v128, v220
	v_mul_f32_e32 v149, v129, v220
	v_mul_f32_e32 v150, v122, v220
	v_mul_f32_e32 v151, v123, v220
	v_mul_f32_e32 v152, v124, v220
	v_mul_f32_e32 v153, v125, v220
	v_add_u32_e32 v156, 0x0, v154
	s_nop 0
	v_cvt_pk_bf16_f32 v206, v146, v147
	v_cvt_pk_bf16_f32 v207, v148, v149
	v_cvt_pk_bf16_f32 v208, v150, v151
	v_cvt_pk_bf16_f32 v209, v152, v153
	global_store_dwordx4 v156, v[206:209], s[24:25]
	v_mul_f32_e32 v146, v92, v220
	v_mul_f32_e32 v147, v93, v220
	v_mul_f32_e32 v148, v94, v220
	v_mul_f32_e32 v149, v95, v220
	v_mul_f32_e32 v150, v88, v220
	v_mul_f32_e32 v151, v89, v220
	v_mul_f32_e32 v152, v90, v220
	v_mul_f32_e32 v153, v91, v220
	v_add_u32_e32 v156, 0x100, v154
	s_nop 0
	v_cvt_pk_bf16_f32 v210, v146, v147
	v_cvt_pk_bf16_f32 v211, v148, v149
	v_cvt_pk_bf16_f32 v212, v150, v151
	v_cvt_pk_bf16_f32 v213, v152, v153
	global_store_dwordx4 v156, v[210:213], s[24:25]
	v_mul_f32_e32 v146, v118, v221
	v_mul_f32_e32 v147, v119, v221
	v_mul_f32_e32 v148, v120, v221
	v_mul_f32_e32 v149, v121, v221
	v_mul_f32_e32 v150, v114, v221
	v_mul_f32_e32 v151, v115, v221
	v_mul_f32_e32 v152, v116, v221
	v_mul_f32_e32 v153, v117, v221
	v_add_u32_e32 v156, 0x4000, v154
	s_nop 0
	v_cvt_pk_bf16_f32 v206, v146, v147
	v_cvt_pk_bf16_f32 v207, v148, v149
	v_cvt_pk_bf16_f32 v208, v150, v151
	v_cvt_pk_bf16_f32 v209, v152, v153
	global_store_dwordx4 v156, v[206:209], s[24:25]
	v_mul_f32_e32 v146, v84, v221
	v_mul_f32_e32 v147, v85, v221
	v_mul_f32_e32 v148, v86, v221
	v_mul_f32_e32 v149, v87, v221
	v_mul_f32_e32 v150, v80, v221
	v_mul_f32_e32 v151, v81, v221
	v_mul_f32_e32 v152, v82, v221
	v_mul_f32_e32 v153, v83, v221
	v_add_u32_e32 v156, 0x4100, v154
	s_nop 0
	v_cvt_pk_bf16_f32 v210, v146, v147
	v_cvt_pk_bf16_f32 v211, v148, v149
	v_cvt_pk_bf16_f32 v212, v150, v151
	v_cvt_pk_bf16_f32 v213, v152, v153
	global_store_dwordx4 v156, v[210:213], s[24:25]
	v_mul_f32_e32 v146, v110, v204
	v_mul_f32_e32 v147, v111, v204
	v_mul_f32_e32 v148, v112, v204
	v_mul_f32_e32 v149, v113, v204
	v_mul_f32_e32 v150, v106, v204
	v_mul_f32_e32 v151, v107, v204
	v_mul_f32_e32 v152, v108, v204
	v_mul_f32_e32 v153, v109, v204
	v_add_u32_e32 v156, 0x8000, v154
	s_nop 0
	v_cvt_pk_bf16_f32 v206, v146, v147
	v_cvt_pk_bf16_f32 v207, v148, v149
	v_cvt_pk_bf16_f32 v208, v150, v151
	v_cvt_pk_bf16_f32 v209, v152, v153
	global_store_dwordx4 v156, v[206:209], s[24:25]
	v_mul_f32_e32 v146, v76, v204
	v_mul_f32_e32 v147, v77, v204
	v_mul_f32_e32 v148, v78, v204
	v_mul_f32_e32 v149, v79, v204
	v_mul_f32_e32 v150, v72, v204
	v_mul_f32_e32 v151, v73, v204
	v_mul_f32_e32 v152, v74, v204
	v_mul_f32_e32 v153, v75, v204
	v_add_u32_e32 v156, 0x8100, v154
	s_nop 0
	v_cvt_pk_bf16_f32 v210, v146, v147
	v_cvt_pk_bf16_f32 v211, v148, v149
	v_cvt_pk_bf16_f32 v212, v150, v151
	v_cvt_pk_bf16_f32 v213, v152, v153
	global_store_dwordx4 v156, v[210:213], s[24:25]
	v_mul_f32_e32 v146, v102, v205
	v_mul_f32_e32 v147, v103, v205
	v_mul_f32_e32 v148, v104, v205
	v_mul_f32_e32 v149, v105, v205
	v_mul_f32_e32 v150, v98, v205
	v_mul_f32_e32 v151, v99, v205
	v_mul_f32_e32 v152, v100, v205
	v_mul_f32_e32 v153, v101, v205
	v_add_u32_e32 v156, 0xc000, v154
	s_nop 0
	v_cvt_pk_bf16_f32 v206, v146, v147
	v_cvt_pk_bf16_f32 v207, v148, v149
	v_cvt_pk_bf16_f32 v208, v150, v151
	v_cvt_pk_bf16_f32 v209, v152, v153
	global_store_dwordx4 v156, v[206:209], s[24:25]
	v_mul_f32_e32 v146, v68, v205
	v_mul_f32_e32 v147, v69, v205
	v_mul_f32_e32 v148, v70, v205
	v_mul_f32_e32 v149, v71, v205
	v_mul_f32_e32 v150, v64, v205
	v_mul_f32_e32 v151, v65, v205
	v_mul_f32_e32 v152, v66, v205
	v_mul_f32_e32 v153, v67, v205
	v_add_u32_e32 v156, 0xc100, v154
	s_nop 0
	v_cvt_pk_bf16_f32 v210, v146, v147
	v_cvt_pk_bf16_f32 v211, v148, v149
	v_cvt_pk_bf16_f32 v212, v150, v151
	v_cvt_pk_bf16_f32 v213, v152, v153
	global_store_dwordx4 v156, v[210:213], s[24:25]
	v_mul_f32_e32 v146, v60, v198
	v_mul_f32_e32 v147, v61, v198
	v_mul_f32_e32 v148, v62, v198
	v_mul_f32_e32 v149, v63, v198
	v_mul_f32_e32 v150, v56, v198
	v_mul_f32_e32 v151, v57, v198
	v_mul_f32_e32 v152, v58, v198
	v_mul_f32_e32 v153, v59, v198
	v_add_u32_e32 v156, 0x20000, v154
	s_nop 0
	v_cvt_pk_bf16_f32 v206, v146, v147
	v_cvt_pk_bf16_f32 v207, v148, v149
	v_cvt_pk_bf16_f32 v208, v150, v151
	v_cvt_pk_bf16_f32 v209, v152, v153
	global_store_dwordx4 v156, v[206:209], s[24:25]
	v_mul_f32_e32 v146, v28, v198
	v_mul_f32_e32 v147, v29, v198
	v_mul_f32_e32 v148, v30, v198
	v_mul_f32_e32 v149, v31, v198
;     DI void operator()(f32x4 (&acc)[2][2][4][2], const Unit& u, int wr, int wc, int fr, int fq, LAS unsigned char* lds) const {
;     ...
;                 int posidx; long offA, offB;
;                 const bool prm = row < TP;
;                 if (prm) { const int b = row >> 13, t = row & 8191; posidx = t;
;                     offA = t >= 8064 ? ((long)(layer * 4 + b) * 128 + (t - 8064)) * 128 : -1;
;                     offB = t >= 7680 ? ((long)(layer * 4 + b) * 512 + (t - 7680)) * 512 : -1;
;                 } else { const int sb = (row - TP) >> 6, t = (row - TP) & 63; posidx = 8192 + t;
;                     offA = ((long)(layer * 32 + sb) * 128 + 64 + t) * 128;
;                     offB = ((long)(layer * 32 + sb) * 512 + 448 + t) * 512; }
; #pragma unroll
;                 for (int bj = 0; bj < 2; ++bj) {
;                     const int gcol = u.pn * 256 + bj * 128;
;                     f32x4 v0 = acc[ai][bj][m][0] * rs, v1 = acc[ai][bj][m][1] * rs;
;                     if (gcol < 768 && gcol != 640) {
;                         if (rope_wave) {
;                             const float* rp = ROPE + (size_t)posidx * 16;
;                             const f32x4 cs0 = *(const f32x4*)rp, cs1 = *(const f32x4*)(rp + 4), sn0 = *(const f32x4*)(rp + 8), sn1 = *(const f32x4*)(rp + 12);
;                             f32x4 p0, p1;
; #pragma unroll
;                             for (int j = 0; j < 4; ++j) { p0[j] = __shfl_xor(v0[j], 16); p1[j] = __shfl_xor(v1[j], 16); }
;                             if (fq == 0) { v0 = v0 * cs0 - p0 * sn0; v1 = v1 * cs1 - p1 * sn1; }
;                             else if (fq == 1) { v0 = v0 * cs0 + p0 * sn0; v1 = v1 * cs1 + p1 * sn1; }
;                         }
;                     }
;                     bf16_t* dst; int ld, c0; float* of = nullptr; long orow = -1;
;                     if (gcol < 512) { dst = QA; ld = 512; c0 = gcol; v0 = v0 * QSCALE; v1 = v1 * QSCALE; }
;                     else if (gcol < 640) { dst = KA; ld = 128; c0 = gcol - 512; of = out + (prm ? O_KWP : O_KWS); orow = offA; }
;                     else if (gcol < 768) { dst = VA; ld = 128; c0 = gcol - 640; of = out + (prm ? O_VWP : O_VWS); orow = offA; }
;                     else if (gcol < 1280) { dst = QB; ld = 512; c0 = gcol - 768; v0 = v0 * QSCALE; v1 = v1 * QSCALE; }
	v_mul_f32_e32 v150, v24, v198
	v_mul_f32_e32 v151, v25, v198
	v_mul_f32_e32 v152, v26, v198
	v_mul_f32_e32 v153, v27, v198
	v_add_u32_e32 v156, 0x20100, v154
	s_nop 0
	v_cvt_pk_bf16_f32 v210, v146, v147
	v_cvt_pk_bf16_f32 v211, v148, v149
	v_cvt_pk_bf16_f32 v212, v150, v151
	v_cvt_pk_bf16_f32 v213, v152, v153
	global_store_dwordx4 v156, v[210:213], s[24:25]
	v_mul_f32_e32 v146, v52, v199
	v_mul_f32_e32 v147, v53, v199
	v_mul_f32_e32 v148, v54, v199
	v_mul_f32_e32 v149, v55, v199
	v_mul_f32_e32 v150, v48, v199
	v_mul_f32_e32 v151, v49, v199
	v_mul_f32_e32 v152, v50, v199
	v_mul_f32_e32 v153, v51, v199
	v_add_u32_e32 v156, 0x24000, v154
	s_nop 0
	v_cvt_pk_bf16_f32 v206, v146, v147
	v_cvt_pk_bf16_f32 v207, v148, v149
	v_cvt_pk_bf16_f32 v208, v150, v151
	v_cvt_pk_bf16_f32 v209, v152, v153
	global_store_dwordx4 v156, v[206:209], s[24:25]
	v_mul_f32_e32 v146, v20, v199
	v_mul_f32_e32 v147, v21, v199
	v_mul_f32_e32 v148, v22, v199
	v_mul_f32_e32 v149, v23, v199
	v_mul_f32_e32 v150, v16, v199
	v_mul_f32_e32 v151, v17, v199
	v_mul_f32_e32 v152, v18, v199
	v_mul_f32_e32 v153, v19, v199
	v_add_u32_e32 v156, 0x24100, v154
	s_nop 0
	v_cvt_pk_bf16_f32 v210, v146, v147
	v_cvt_pk_bf16_f32 v211, v148, v149
	v_cvt_pk_bf16_f32 v212, v150, v151
	v_cvt_pk_bf16_f32 v213, v152, v153
	global_store_dwordx4 v156, v[210:213], s[24:25]
	v_mul_f32_e32 v146, v44, v194
	v_mul_f32_e32 v147, v45, v194
	v_mul_f32_e32 v148, v46, v194
	v_mul_f32_e32 v149, v47, v194
	v_mul_f32_e32 v150, v40, v194
	v_mul_f32_e32 v151, v41, v194
	v_mul_f32_e32 v152, v42, v194
	v_mul_f32_e32 v153, v43, v194
	v_add_u32_e32 v156, 0x28000, v154
	s_nop 0
	v_cvt_pk_bf16_f32 v206, v146, v147
	v_cvt_pk_bf16_f32 v207, v148, v149
	v_cvt_pk_bf16_f32 v208, v150, v151
	v_cvt_pk_bf16_f32 v209, v152, v153
	global_store_dwordx4 v156, v[206:209], s[24:25]
	v_mul_f32_e32 v146, v12, v194
	v_mul_f32_e32 v147, v13, v194
	v_mul_f32_e32 v148, v14, v194
	v_mul_f32_e32 v149, v15, v194
	v_mul_f32_e32 v150, v8, v194
	v_mul_f32_e32 v151, v9, v194
	v_mul_f32_e32 v152, v10, v194
	v_mul_f32_e32 v153, v11, v194
	v_add_u32_e32 v156, 0x28100, v154
	s_nop 0
	v_cvt_pk_bf16_f32 v210, v146, v147
	v_cvt_pk_bf16_f32 v211, v148, v149
	v_cvt_pk_bf16_f32 v212, v150, v151
	v_cvt_pk_bf16_f32 v213, v152, v153
	global_store_dwordx4 v156, v[210:213], s[24:25]
	v_mul_f32_e32 v146, v36, v195
	v_mul_f32_e32 v147, v37, v195
	v_mul_f32_e32 v148, v38, v195
	v_mul_f32_e32 v149, v39, v195
	v_mul_f32_e32 v150, v32, v195
	v_mul_f32_e32 v151, v33, v195
	v_mul_f32_e32 v152, v34, v195
	v_mul_f32_e32 v153, v35, v195
	v_add_u32_e32 v156, 0x2c000, v154
	s_nop 0
	v_cvt_pk_bf16_f32 v206, v146, v147
	v_cvt_pk_bf16_f32 v207, v148, v149
	v_cvt_pk_bf16_f32 v208, v150, v151
	v_cvt_pk_bf16_f32 v209, v152, v153
	global_store_dwordx4 v156, v[206:209], s[24:25]
	v_mul_f32_e32 v146, v4, v195
	v_mul_f32_e32 v147, v5, v195
	v_mul_f32_e32 v148, v6, v195
	v_mul_f32_e32 v149, v7, v195
	v_mul_f32_e32 v150, v0, v195
	v_mul_f32_e32 v151, v1, v195
	v_mul_f32_e32 v152, v2, v195
	v_mul_f32_e32 v153, v3, v195
	v_add_u32_e32 v156, 0x2c100, v154
	s_nop 0
	v_cvt_pk_bf16_f32 v210, v146, v147
	v_cvt_pk_bf16_f32 v211, v148, v149
	v_cvt_pk_bf16_f32 v212, v150, v151
	v_cvt_pk_bf16_f32 v213, v152, v153
	global_store_dwordx4 v156, v[210:213], s[24:25]
	s_mov_b64 s[22:23], exec
	s_branch .LBB0_639
.Lepf_kv_sample:
	v_readlane_b32 s23, v246, 32
	s_add_i32 s0, s96, 0xffffff80
	s_lshl_b32 s0, s0, 2
	s_add_i32 s23, s23, s0
	s_lshl_b32 s23, s23, 9
	s_addk_i32 s23, 0x1c0
	s_lshl_b32 s23, s23, 9
	s_add_i32 s23, s23, s27
	s_lshr_b32 s0, s22, 1
	s_add_i32 s23, s23, s0
	s_mov_b32 s28, 0x200000
	v_lshrrev_b32_e32 v155, 6, v171
	v_and_b32_e32 v157, 63, v171
	v_lshl_add_u32 v155, v155, 9, v157
	v_lshl_add_u32 v155, v155, 9, v166
	s_branch .Lepf_kv_side
.Lepf_kv_tail:
	s_lshr_b32 s23, s96, 5
	s_add_i32 s23, s23, s92
	s_lshl_b32 s23, s23, 9
	s_and_b32 s0, s96, 31
	s_add_i32 s0, s0, -30
	s_lshl_b32 s0, s0, 8
	s_add_i32 s23, s23, s0
	s_lshl_b32 s23, s23, 9
	s_add_i32 s23, s23, s26
	s_lshr_b32 s0, s22, 1
	s_add_i32 s23, s23, s0
	s_mov_b32 s28, 0x40000
	v_lshl_add_u32 v155, v171, 9, v166
.Lepf_kv_side:
	v_add_u32_e32 v155, s23, v155
	v_lshlrev_b32_e32 v155, 2, v155
	v_add_u32_e32 v157, s28, v155
	s_waitcnt lgkmcnt(0)
	v_lshlrev_b32_e32 v154, 10, v192
	v_lshl_add_u32 v154, v166, 1, v154
	v_add_u32_e32 v154, s22, v154
	v_mul_f32_e32 v146, v126, v220
	v_mul_f32_e32 v147, v127, v220
	v_mul_f32_e32 v148, v128, v220
	v_mul_f32_e32 v149, v129, v220
	v_mul_f32_e32 v150, v122, v220
	v_mul_f32_e32 v151, v123, v220
	v_mul_f32_e32 v152, v124, v220
	v_mul_f32_e32 v153, v125, v220
	v_add_u32_e32 v156, 0x0, v154
	v_add_u32_e32 v200, 0x0, v155
	v_cvt_pk_bf16_f32 v206, v146, v147
	v_cvt_pk_bf16_f32 v207, v148, v149
	v_cvt_pk_bf16_f32 v208, v150, v151
	v_cvt_pk_bf16_f32 v209, v152, v153
	global_store_dwordx4 v156, v[206:209], s[24:25]
	global_store_dwordx4 v200, v[146:149], s[90:91]
	global_store_dwordx4 v200, v[150:153], s[90:91] offset:16
	v_mul_f32_e32 v236, v92, v220
	v_mul_f32_e32 v237, v93, v220
	v_mul_f32_e32 v238, v94, v220
	v_mul_f32_e32 v239, v95, v220
	v_mul_f32_e32 v240, v88, v220
	v_mul_f32_e32 v241, v89, v220
	v_mul_f32_e32 v242, v90, v220
	v_mul_f32_e32 v243, v91, v220
	v_add_u32_e32 v156, 0x100, v154
	v_add_u32_e32 v200, 0x200, v155
	v_cvt_pk_bf16_f32 v210, v236, v237
	v_cvt_pk_bf16_f32 v211, v238, v239
	v_cvt_pk_bf16_f32 v212, v240, v241
	v_cvt_pk_bf16_f32 v213, v242, v243
	global_store_dwordx4 v156, v[210:213], s[24:25]
	global_store_dwordx4 v200, v[236:239], s[90:91]
	global_store_dwordx4 v200, v[240:243], s[90:91] offset:16
	v_mul_f32_e32 v146, v118, v221
	v_mul_f32_e32 v147, v119, v221
; DI unsigned pk2(float lo, float hi) { f32x2 v = {lo, hi}; hbf2 r = __builtin_convertvector(v, hbf2); return __builtin_bit_cast(unsigned, r); }
;     DI void operator()(f32x4 (&acc)[2][2][4][2], const Unit& u, int wr, int wc, int fr, int fq, LAS unsigned char* lds) const {
;     ...
;                     u32x4 w; w.x = pk2(v0[0], v0[1]); w.y = pk2(v0[2], v0[3]); w.z = pk2(v1[0], v1[1]); w.w = pk2(v1[2], v1[3]);
;                     *(u32x4*)(dst + (size_t)row * ld + c0 + cw) = w;
;                     if (of != nullptr && orow >= 0) { float* op = of + orow + c0 + cw; *(f32x4*)op = v0; *(f32x4*)(op + 4) = v1; }
	v_mul_f32_e32 v148, v120, v221
	v_mul_f32_e32 v149, v121, v221
	v_mul_f32_e32 v150, v114, v221
	v_mul_f32_e32 v151, v115, v221
	v_mul_f32_e32 v152, v116, v221
	v_mul_f32_e32 v153, v117, v221
	v_add_u32_e32 v156, 0x4000, v154
	v_add_u32_e32 v200, 0x8000, v155
	v_cvt_pk_bf16_f32 v206, v146, v147
	v_cvt_pk_bf16_f32 v207, v148, v149
	v_cvt_pk_bf16_f32 v208, v150, v151
	v_cvt_pk_bf16_f32 v209, v152, v153
	global_store_dwordx4 v156, v[206:209], s[24:25]
	global_store_dwordx4 v200, v[146:149], s[90:91]
	global_store_dwordx4 v200, v[150:153], s[90:91] offset:16
	v_mul_f32_e32 v236, v84, v221
	v_mul_f32_e32 v237, v85, v221
	v_mul_f32_e32 v238, v86, v221
	v_mul_f32_e32 v239, v87, v221
	v_mul_f32_e32 v240, v80, v221
	v_mul_f32_e32 v241, v81, v221
	v_mul_f32_e32 v242, v82, v221
	v_mul_f32_e32 v243, v83, v221
	v_add_u32_e32 v156, 0x4100, v154
	v_add_u32_e32 v200, 0x8200, v155
	v_cvt_pk_bf16_f32 v210, v236, v237
	v_cvt_pk_bf16_f32 v211, v238, v239
	v_cvt_pk_bf16_f32 v212, v240, v241
	v_cvt_pk_bf16_f32 v213, v242, v243
	global_store_dwordx4 v156, v[210:213], s[24:25]
	global_store_dwordx4 v200, v[236:239], s[90:91]
	global_store_dwordx4 v200, v[240:243], s[90:91] offset:16
	v_mul_f32_e32 v146, v110, v204
	v_mul_f32_e32 v147, v111, v204
	v_mul_f32_e32 v148, v112, v204
	v_mul_f32_e32 v149, v113, v204
	v_mul_f32_e32 v150, v106, v204
	v_mul_f32_e32 v151, v107, v204
	v_mul_f32_e32 v152, v108, v204
	v_mul_f32_e32 v153, v109, v204
	v_add_u32_e32 v156, 0x8000, v154
	v_add_u32_e32 v200, 0x10000, v155
	v_cvt_pk_bf16_f32 v206, v146, v147
	v_cvt_pk_bf16_f32 v207, v148, v149
	v_cvt_pk_bf16_f32 v208, v150, v151
	v_cvt_pk_bf16_f32 v209, v152, v153
	global_store_dwordx4 v156, v[206:209], s[24:25]
	global_store_dwordx4 v200, v[146:149], s[90:91]
	global_store_dwordx4 v200, v[150:153], s[90:91] offset:16
	v_mul_f32_e32 v236, v76, v204
	v_mul_f32_e32 v237, v77, v204
	v_mul_f32_e32 v238, v78, v204
	v_mul_f32_e32 v239, v79, v204
	v_mul_f32_e32 v240, v72, v204
	v_mul_f32_e32 v241, v73, v204
	v_mul_f32_e32 v242, v74, v204
	v_mul_f32_e32 v243, v75, v204
	v_add_u32_e32 v156, 0x8100, v154
	v_add_u32_e32 v200, 0x10200, v155
	v_cvt_pk_bf16_f32 v210, v236, v237
	v_cvt_pk_bf16_f32 v211, v238, v239
	v_cvt_pk_bf16_f32 v212, v240, v241
	v_cvt_pk_bf16_f32 v213, v242, v243
	global_store_dwordx4 v156, v[210:213], s[24:25]
	global_store_dwordx4 v200, v[236:239], s[90:91]
	global_store_dwordx4 v200, v[240:243], s[90:91] offset:16
	v_mul_f32_e32 v146, v102, v205
	v_mul_f32_e32 v147, v103, v205
	v_mul_f32_e32 v148, v104, v205
	v_mul_f32_e32 v149, v105, v205
	v_mul_f32_e32 v150, v98, v205
	v_mul_f32_e32 v151, v99, v205
	v_mul_f32_e32 v152, v100, v205
	v_mul_f32_e32 v153, v101, v205
	v_add_u32_e32 v156, 0xc000, v154
	v_add_u32_e32 v200, 0x18000, v155
	v_cvt_pk_bf16_f32 v206, v146, v147
	v_cvt_pk_bf16_f32 v207, v148, v149
	v_cvt_pk_bf16_f32 v208, v150, v151
	v_cvt_pk_bf16_f32 v209, v152, v153
	global_store_dwordx4 v156, v[206:209], s[24:25]
	global_store_dwordx4 v200, v[146:149], s[90:91]
	global_store_dwordx4 v200, v[150:153], s[90:91] offset:16
	v_mul_f32_e32 v236, v68, v205
	v_mul_f32_e32 v237, v69, v205
	v_mul_f32_e32 v238, v70, v205
	v_mul_f32_e32 v239, v71, v205
	v_mul_f32_e32 v240, v64, v205
	v_mul_f32_e32 v241, v65, v205
	v_mul_f32_e32 v242, v66, v205
	v_mul_f32_e32 v243, v67, v205
	v_add_u32_e32 v156, 0xc100, v154
	v_add_u32_e32 v200, 0x18200, v155
	v_cvt_pk_bf16_f32 v210, v236, v237
	v_cvt_pk_bf16_f32 v211, v238, v239
	v_cvt_pk_bf16_f32 v212, v240, v241
	v_cvt_pk_bf16_f32 v213, v242, v243
	global_store_dwordx4 v156, v[210:213], s[24:25]
	global_store_dwordx4 v200, v[236:239], s[90:91]
	global_store_dwordx4 v200, v[240:243], s[90:91] offset:16
	v_mul_f32_e32 v146, v60, v198
	v_mul_f32_e32 v147, v61, v198
	v_mul_f32_e32 v148, v62, v198
	v_mul_f32_e32 v149, v63, v198
	v_mul_f32_e32 v150, v56, v198
	v_mul_f32_e32 v151, v57, v198
	v_mul_f32_e32 v152, v58, v198
	v_mul_f32_e32 v153, v59, v198
	v_add_u32_e32 v156, 0x20000, v154
	v_add_u32_e32 v200, 0x0, v157
	v_cvt_pk_bf16_f32 v206, v146, v147
	v_cvt_pk_bf16_f32 v207, v148, v149
	v_cvt_pk_bf16_f32 v208, v150, v151
	v_cvt_pk_bf16_f32 v209, v152, v153
	global_store_dwordx4 v156, v[206:209], s[24:25]
	global_store_dwordx4 v200, v[146:149], s[90:91]
	global_store_dwordx4 v200, v[150:153], s[90:91] offset:16
	v_mul_f32_e32 v236, v28, v198
; DI unsigned pk2(float lo, float hi) { f32x2 v = {lo, hi}; hbf2 r = __builtin_convertvector(v, hbf2); return __builtin_bit_cast(unsigned, r); }
;     DI void operator()(f32x4 (&acc)[2][2][4][2], const Unit& u, int wr, int wc, int fr, int fq, LAS unsigned char* lds) const {
;     ...
;                     u32x4 w; w.x = pk2(v0[0], v0[1]); w.y = pk2(v0[2], v0[3]); w.z = pk2(v1[0], v1[1]); w.w = pk2(v1[2], v1[3]);
;                     *(u32x4*)(dst + (size_t)row * ld + c0 + cw) = w;
;                     if (of != nullptr && orow >= 0) { float* op = of + orow + c0 + cw; *(f32x4*)op = v0; *(f32x4*)(op + 4) = v1; }
	v_mul_f32_e32 v237, v29, v198
	v_mul_f32_e32 v238, v30, v198
	v_mul_f32_e32 v239, v31, v198
	v_mul_f32_e32 v240, v24, v198
	v_mul_f32_e32 v241, v25, v198
	v_mul_f32_e32 v242, v26, v198
	v_mul_f32_e32 v243, v27, v198
	v_add_u32_e32 v156, 0x20100, v154
	v_add_u32_e32 v200, 0x200, v157
	v_cvt_pk_bf16_f32 v210, v236, v237
	v_cvt_pk_bf16_f32 v211, v238, v239
	v_cvt_pk_bf16_f32 v212, v240, v241
	v_cvt_pk_bf16_f32 v213, v242, v243
	global_store_dwordx4 v156, v[210:213], s[24:25]
	global_store_dwordx4 v200, v[236:239], s[90:91]
	global_store_dwordx4 v200, v[240:243], s[90:91] offset:16
	v_mul_f32_e32 v146, v52, v199
	v_mul_f32_e32 v147, v53, v199
	v_mul_f32_e32 v148, v54, v199
	v_mul_f32_e32 v149, v55, v199
	v_mul_f32_e32 v150, v48, v199
	v_mul_f32_e32 v151, v49, v199
	v_mul_f32_e32 v152, v50, v199
	v_mul_f32_e32 v153, v51, v199
	v_add_u32_e32 v156, 0x24000, v154
	v_add_u32_e32 v200, 0x8000, v157
	v_cvt_pk_bf16_f32 v206, v146, v147
	v_cvt_pk_bf16_f32 v207, v148, v149
	v_cvt_pk_bf16_f32 v208, v150, v151
	v_cvt_pk_bf16_f32 v209, v152, v153
	global_store_dwordx4 v156, v[206:209], s[24:25]
	global_store_dwordx4 v200, v[146:149], s[90:91]
	global_store_dwordx4 v200, v[150:153], s[90:91] offset:16
	v_mul_f32_e32 v236, v20, v199
	v_mul_f32_e32 v237, v21, v199
	v_mul_f32_e32 v238, v22, v199
	v_mul_f32_e32 v239, v23, v199
	v_mul_f32_e32 v240, v16, v199
	v_mul_f32_e32 v241, v17, v199
	v_mul_f32_e32 v242, v18, v199
	v_mul_f32_e32 v243, v19, v199
	v_add_u32_e32 v156, 0x24100, v154
	v_add_u32_e32 v200, 0x8200, v157
	v_cvt_pk_bf16_f32 v210, v236, v237
	v_cvt_pk_bf16_f32 v211, v238, v239
	v_cvt_pk_bf16_f32 v212, v240, v241
	v_cvt_pk_bf16_f32 v213, v242, v243
	global_store_dwordx4 v156, v[210:213], s[24:25]
	global_store_dwordx4 v200, v[236:239], s[90:91]
	global_store_dwordx4 v200, v[240:243], s[90:91] offset:16
	v_mul_f32_e32 v146, v44, v194
	v_mul_f32_e32 v147, v45, v194
	v_mul_f32_e32 v148, v46, v194
	v_mul_f32_e32 v149, v47, v194
	v_mul_f32_e32 v150, v40, v194
	v_mul_f32_e32 v151, v41, v194
	v_mul_f32_e32 v152, v42, v194
	v_mul_f32_e32 v153, v43, v194
	v_add_u32_e32 v156, 0x28000, v154
	v_add_u32_e32 v200, 0x10000, v157
	v_cvt_pk_bf16_f32 v206, v146, v147
	v_cvt_pk_bf16_f32 v207, v148, v149
	v_cvt_pk_bf16_f32 v208, v150, v151
	v_cvt_pk_bf16_f32 v209, v152, v153
	global_store_dwordx4 v156, v[206:209], s[24:25]
	global_store_dwordx4 v200, v[146:149], s[90:91]
	global_store_dwordx4 v200, v[150:153], s[90:91] offset:16
	v_mul_f32_e32 v236, v12, v194
	v_mul_f32_e32 v237, v13, v194
	v_mul_f32_e32 v238, v14, v194
	v_mul_f32_e32 v239, v15, v194
	v_mul_f32_e32 v240, v8, v194
	v_mul_f32_e32 v241, v9, v194
	v_mul_f32_e32 v242, v10, v194
	v_mul_f32_e32 v243, v11, v194
	v_add_u32_e32 v156, 0x28100, v154
	v_add_u32_e32 v200, 0x10200, v157
	v_cvt_pk_bf16_f32 v210, v236, v237
	v_cvt_pk_bf16_f32 v211, v238, v239
	v_cvt_pk_bf16_f32 v212, v240, v241
	v_cvt_pk_bf16_f32 v213, v242, v243
	global_store_dwordx4 v156, v[210:213], s[24:25]
	global_store_dwordx4 v200, v[236:239], s[90:91]
	global_store_dwordx4 v200, v[240:243], s[90:91] offset:16
	v_mul_f32_e32 v146, v36, v195
	v_mul_f32_e32 v147, v37, v195
	v_mul_f32_e32 v148, v38, v195
	v_mul_f32_e32 v149, v39, v195
	v_mul_f32_e32 v150, v32, v195
	v_mul_f32_e32 v151, v33, v195
	v_mul_f32_e32 v152, v34, v195
	v_mul_f32_e32 v153, v35, v195
	v_add_u32_e32 v156, 0x2c000, v154
	v_add_u32_e32 v200, 0x18000, v157
	v_cvt_pk_bf16_f32 v206, v146, v147
	v_cvt_pk_bf16_f32 v207, v148, v149
	v_cvt_pk_bf16_f32 v208, v150, v151
	v_cvt_pk_bf16_f32 v209, v152, v153
	global_store_dwordx4 v156, v[206:209], s[24:25]
	global_store_dwordx4 v200, v[146:149], s[90:91]
	global_store_dwordx4 v200, v[150:153], s[90:91] offset:16
	v_mul_f32_e32 v236, v4, v195
	v_mul_f32_e32 v237, v5, v195
	v_mul_f32_e32 v238, v6, v195
	v_mul_f32_e32 v239, v7, v195
	v_mul_f32_e32 v240, v0, v195
	v_mul_f32_e32 v241, v1, v195
	v_mul_f32_e32 v242, v2, v195
	v_mul_f32_e32 v243, v3, v195
	v_add_u32_e32 v156, 0x2c100, v154
	v_add_u32_e32 v200, 0x18200, v157
	v_cvt_pk_bf16_f32 v210, v236, v237
	v_cvt_pk_bf16_f32 v211, v238, v239
	v_cvt_pk_bf16_f32 v212, v240, v241
	v_cvt_pk_bf16_f32 v213, v242, v243
	global_store_dwordx4 v156, v[210:213], s[24:25]
	global_store_dwordx4 v200, v[236:239], s[90:91]
	global_store_dwordx4 v200, v[240:243], s[90:91] offset:16
	s_mov_b64 s[22:23], exec
	s_branch .LBB0_639
